# QKV epilogue V tiles: 16x16 transpose through wave-private LDS slot, 16B stores instead of 128 2-byte stores per lane; plus previous edits
# speedup vs baseline: 1.0131x; 1.0091x over previous
; #define LAS __attribute__((address_space(3)))
;     __device__ __forceinline__ void operator()(f32x4 (&acc)[2][2][4][2], const Unit& u, int wr, int wc, int fr, int fq) const {
;         const int row0 = u.pm * BM + wr * 64 + fr, vb = u.pn * BM + wc * 32 + 8 * fq;
;         {
;             float mu[2][4], rs[2][4]; f32x4 w[2][2], c[2][2];
;             const LAS float* slot = vl + (wr * 4 + wc) * 512;
;             lnfold_rows(slot, fr, mu, rs); (void)vb;
; #pragma unroll
;             for (int bj = 0; bj < 2; ++bj)
; #pragma unroll
;                 for (int n = 0; n < 2; ++n) { w[bj][n] = *(const LAS f32x4*)(slot + 256 + bj * 32 + 8 * fq + 4 * n); c[bj][n] = *(const LAS f32x4*)(slot + 320 + bj * 32 + 8 * fq + 4 * n); }
;             if (u.pn < 8) {
;                 const float qs = 0.08838834764831845f * 1.4426950408889634f;
; #pragma unroll
;                 for (int i = 0; i < 8; ++i) rs[i >> 2][i & 3] *= qs;
; #pragma unroll
;                 for (int bj = 0; bj < 2; ++bj)
; #pragma unroll
;                     for (int n = 0; n < 2; ++n) c[bj][n] *= qs;
;             }
; #pragma unroll
;             for (int ai = 0; ai < 2; ++ai)
; #pragma unroll
;                 for (int m = 0; m < 4; ++m)
; #pragma unroll
;                     for (int bj = 0; bj < 2; ++bj)
; #pragma unroll
;                         for (int n = 0; n < 2; ++n) acc[ai][bj][m][n] = (acc[ai][bj][m][n] - mu[ai][m] * w[bj][n]) * rs[ai][m] + c[bj][n];
.LBB0_203:
	s_waitcnt lgkmcnt(0)
	v_pk_fma_f32 v[108:109], v[188:189], v[132:133], v[108:109] op_sel_hi:[0,1,1] neg_lo:[1,0,0] neg_hi:[1,0,0]
	v_pk_fma_f32 v[92:93], v[192:193], v[132:133], v[92:93] op_sel_hi:[0,1,1] neg_lo:[1,0,0] neg_hi:[1,0,0]
	v_pk_fma_f32 v[76:77], v[202:203], v[132:133], v[76:77] op_sel_hi:[0,1,1] neg_lo:[1,0,0] neg_hi:[1,0,0]
	v_pk_fma_f32 v[128:129], v[188:189], v[156:157], v[128:129] op_sel_hi:[0,1,1] neg_lo:[1,0,0] neg_hi:[1,0,0]
	v_pk_fma_f32 v[124:125], v[188:189], v[148:149], v[124:125] op_sel_hi:[0,1,1] neg_lo:[1,0,0] neg_hi:[1,0,0]
	v_pk_fma_f32 v[106:107], v[188:189], v[130:131], v[106:107] op_sel_hi:[0,1,1] neg_lo:[1,0,0] neg_hi:[1,0,0]
	v_pk_fma_f32 v[190:191], v[108:109], v[200:201], v[144:145] op_sel_hi:[1,0,1]
	v_pk_fma_f32 v[108:109], v[192:193], v[156:157], v[120:121] op_sel_hi:[0,1,1] neg_lo:[1,0,0] neg_hi:[1,0,0]
	v_pk_fma_f32 v[112:113], v[192:193], v[148:149], v[112:113] op_sel_hi:[0,1,1] neg_lo:[1,0,0] neg_hi:[1,0,0]
	v_pk_fma_f32 v[90:91], v[192:193], v[130:131], v[90:91] op_sel_hi:[0,1,1] neg_lo:[1,0,0] neg_hi:[1,0,0]
	v_pk_fma_f32 v[120:121], v[92:93], v[200:201], v[144:145] op_sel:[0,1,0]
	v_pk_fma_f32 v[92:93], v[202:203], v[156:157], v[104:105] op_sel_hi:[0,1,1] neg_lo:[1,0,0] neg_hi:[1,0,0]
	v_pk_fma_f32 v[100:101], v[202:203], v[148:149], v[100:101] op_sel_hi:[0,1,1] neg_lo:[1,0,0] neg_hi:[1,0,0]
	v_pk_fma_f32 v[74:75], v[202:203], v[130:131], v[74:75] op_sel_hi:[0,1,1] neg_lo:[1,0,0] neg_hi:[1,0,0]
	v_pk_fma_f32 v[104:105], v[76:77], v[198:199], v[144:145] op_sel_hi:[1,0,1]
	v_pk_fma_f32 v[76:77], v[194:195], v[156:157], v[88:89] op_sel_hi:[0,1,1] neg_lo:[1,0,0] neg_hi:[1,0,0]
	v_pk_fma_f32 v[84:85], v[194:195], v[148:149], v[84:85] op_sel_hi:[0,1,1] neg_lo:[1,0,0] neg_hi:[1,0,0]
	v_xor_b32_e32 v157, 0x80000000, v157
	v_xor_b32_e32 v156, 0x80000000, v156
	v_pk_fma_f32 v[60:61], v[208:209], v[148:149], v[60:61] op_sel_hi:[0,1,1] neg_lo:[1,0,0] neg_hi:[1,0,0]
	v_pk_fma_f32 v[44:45], v[208:209], v[132:133], v[44:45] op_sel_hi:[0,1,1] neg_lo:[1,0,0] neg_hi:[1,0,0]
	v_pk_fma_f32 v[42:43], v[208:209], v[130:131], v[42:43] op_sel_hi:[0,1,1] neg_lo:[1,0,0] neg_hi:[1,0,0]
	v_pk_fma_f32 v[52:53], v[196:197], v[148:149], v[52:53] op_sel_hi:[0,1,1] neg_lo:[1,0,0] neg_hi:[1,0,0]
	v_pk_fma_f32 v[28:29], v[196:197], v[132:133], v[28:29] op_sel_hi:[0,1,1] neg_lo:[1,0,0] neg_hi:[1,0,0]
	v_pk_fma_f32 v[26:27], v[196:197], v[130:131], v[26:27] op_sel_hi:[0,1,1] neg_lo:[1,0,0] neg_hi:[1,0,0]
	v_xor_b32_e32 v149, 0x80000000, v149
	v_xor_b32_e32 v148, 0x80000000, v148
	v_pk_fma_f32 v[12:13], v[210:211], v[132:133], v[12:13] op_sel_hi:[0,1,1] neg_lo:[1,0,0] neg_hi:[1,0,0]
	v_pk_fma_f32 v[10:11], v[210:211], v[130:131], v[10:11] op_sel_hi:[0,1,1] neg_lo:[1,0,0] neg_hi:[1,0,0]
	v_add_u32_e32 v186, s37, v1
	v_pk_fma_f32 v[126:127], v[188:189], v[154:155], v[126:127] op_sel_hi:[0,1,1] neg_lo:[1,0,0] neg_hi:[1,0,0]
	v_pk_fma_f32 v[122:123], v[188:189], v[146:147], v[122:123] op_sel_hi:[0,1,1] neg_lo:[1,0,0] neg_hi:[1,0,0]
	v_pk_fma_f32 v[116:117], v[188:189], v[140:141], v[116:117] op_sel_hi:[0,1,1] neg_lo:[1,0,0] neg_hi:[1,0,0]
	v_pk_fma_f32 v[114:115], v[188:189], v[138:139], v[114:115] op_sel_hi:[0,1,1] neg_lo:[1,0,0] neg_hi:[1,0,0]
	v_pk_fma_f32 v[188:189], v[106:107], v[200:201], v[142:143] op_sel_hi:[1,0,1]
	v_pk_fma_f32 v[106:107], v[192:193], v[154:155], v[118:119] op_sel_hi:[0,1,1] neg_lo:[1,0,0] neg_hi:[1,0,0]
	v_pk_fma_f32 v[110:111], v[192:193], v[146:147], v[110:111] op_sel_hi:[0,1,1] neg_lo:[1,0,0] neg_hi:[1,0,0]
	v_pk_fma_f32 v[96:97], v[192:193], v[140:141], v[96:97] op_sel_hi:[0,1,1] neg_lo:[1,0,0] neg_hi:[1,0,0]
	v_pk_fma_f32 v[94:95], v[192:193], v[138:139], v[94:95] op_sel_hi:[0,1,1] neg_lo:[1,0,0] neg_hi:[1,0,0]
	v_pk_fma_f32 v[118:119], v[90:91], v[200:201], v[142:143] op_sel:[0,1,0]
	v_pk_fma_f32 v[90:91], v[202:203], v[154:155], v[102:103] op_sel_hi:[0,1,1] neg_lo:[1,0,0] neg_hi:[1,0,0]
	v_pk_fma_f32 v[98:99], v[202:203], v[146:147], v[98:99] op_sel_hi:[0,1,1] neg_lo:[1,0,0] neg_hi:[1,0,0]
	v_pk_fma_f32 v[80:81], v[202:203], v[140:141], v[80:81] op_sel_hi:[0,1,1] neg_lo:[1,0,0] neg_hi:[1,0,0]
	v_pk_fma_f32 v[78:79], v[202:203], v[138:139], v[78:79] op_sel_hi:[0,1,1] neg_lo:[1,0,0] neg_hi:[1,0,0]
	v_pk_fma_f32 v[102:103], v[74:75], v[198:199], v[142:143] op_sel_hi:[1,0,1]
	v_pk_fma_f32 v[74:75], v[194:195], v[154:155], v[86:87] op_sel_hi:[0,1,1] neg_lo:[1,0,0] neg_hi:[1,0,0]
	v_pk_fma_f32 v[82:83], v[194:195], v[146:147], v[82:83] op_sel_hi:[0,1,1] neg_lo:[1,0,0] neg_hi:[1,0,0]
	v_pk_fma_f32 v[72:73], v[194:195], v[140:141], v[72:73] op_sel_hi:[0,1,1] neg_lo:[1,0,0] neg_hi:[1,0,0]
	v_pk_fma_f32 v[70:71], v[194:195], v[138:139], v[70:71] op_sel_hi:[0,1,1] neg_lo:[1,0,0] neg_hi:[1,0,0]
	v_pk_fma_f32 v[68:69], v[194:195], v[132:133], v[68:69] op_sel_hi:[0,1,1] neg_lo:[1,0,0] neg_hi:[1,0,0]
	v_pk_fma_f32 v[66:67], v[194:195], v[130:131], v[66:67] op_sel_hi:[0,1,1] neg_lo:[1,0,0] neg_hi:[1,0,0]
	v_pk_fma_f32 v[64:65], v[156:157], v[208:209], v[64:65] op_sel_hi:[1,0,1]
	v_pk_fma_f32 v[62:63], v[154:155], v[208:209], v[62:63] op_sel_hi:[1,0,1] neg_lo:[1,0,0] neg_hi:[1,0,0]
	v_pk_fma_f32 v[58:59], v[208:209], v[146:147], v[58:59] op_sel_hi:[0,1,1] neg_lo:[1,0,0] neg_hi:[1,0,0]
	v_pk_fma_f32 v[48:49], v[208:209], v[140:141], v[48:49] op_sel_hi:[0,1,1] neg_lo:[1,0,0] neg_hi:[1,0,0]
	v_pk_fma_f32 v[46:47], v[208:209], v[138:139], v[46:47] op_sel_hi:[0,1,1] neg_lo:[1,0,0] neg_hi:[1,0,0]
	v_pk_fma_f32 v[86:87], v[42:43], v[206:207], v[142:143] op_sel_hi:[1,0,1]
	v_pk_fma_f32 v[88:89], v[44:45], v[206:207], v[144:145] op_sel_hi:[1,0,1]
	v_pk_fma_f32 v[44:45], v[156:157], v[196:197], v[56:57] op_sel_hi:[1,0,1]
;     __device__ __forceinline__ void operator()(f32x4 (&acc)[2][2][4][2], const Unit& u, int wr, int wc, int fr, int fq) const {
;     ...
; #pragma unroll
;             for (int ai = 0; ai < 2; ++ai)
; #pragma unroll
;                 for (int m = 0; m < 4; ++m)
; #pragma unroll
;                     for (int bj = 0; bj < 2; ++bj)
; #pragma unroll
;                         for (int n = 0; n < 2; ++n) acc[ai][bj][m][n] = (acc[ai][bj][m][n] - mu[ai][m] * w[bj][n]) * rs[ai][m] + c[bj][n];
;         }
;         if (u.pn < 10) {
	v_pk_fma_f32 v[42:43], v[154:155], v[196:197], v[54:55] op_sel_hi:[1,0,1] neg_lo:[1,0,0] neg_hi:[1,0,0]
	v_pk_fma_f32 v[50:51], v[196:197], v[146:147], v[50:51] op_sel_hi:[0,1,1] neg_lo:[1,0,0] neg_hi:[1,0,0]
	v_pk_fma_f32 v[36:37], v[196:197], v[140:141], v[36:37] op_sel_hi:[0,1,1] neg_lo:[1,0,0] neg_hi:[1,0,0]
	v_pk_fma_f32 v[34:35], v[196:197], v[138:139], v[34:35] op_sel_hi:[0,1,1] neg_lo:[1,0,0] neg_hi:[1,0,0]
	v_pk_fma_f32 v[54:55], v[26:27], v[206:207], v[142:143] op_sel:[0,1,0]
	v_pk_fma_f32 v[56:57], v[28:29], v[206:207], v[144:145] op_sel:[0,1,0]
	v_pk_fma_f32 v[28:29], v[156:157], v[210:211], v[40:41] op_sel_hi:[1,0,1]
	v_pk_fma_f32 v[26:27], v[154:155], v[210:211], v[38:39] op_sel_hi:[1,0,1] neg_lo:[1,0,0] neg_hi:[1,0,0]
	v_pk_fma_f32 v[32:33], v[148:149], v[210:211], v[32:33] op_sel_hi:[1,0,1]
	v_pk_fma_f32 v[30:31], v[146:147], v[210:211], v[30:31] op_sel_hi:[1,0,1] neg_lo:[1,0,0] neg_hi:[1,0,0]
	v_pk_fma_f32 v[16:17], v[210:211], v[140:141], v[16:17] op_sel_hi:[0,1,1] neg_lo:[1,0,0] neg_hi:[1,0,0]
	v_pk_fma_f32 v[14:15], v[210:211], v[138:139], v[14:15] op_sel_hi:[0,1,1] neg_lo:[1,0,0] neg_hi:[1,0,0]
	v_pk_fma_f32 v[38:39], v[10:11], v[212:213], v[142:143] op_sel_hi:[1,0,1]
	v_pk_fma_f32 v[40:41], v[12:13], v[212:213], v[144:145] op_sel_hi:[1,0,1]
	v_pk_fma_f32 v[12:13], v[156:157], v[204:205], v[24:25] op_sel_hi:[1,0,1]
	v_pk_fma_f32 v[10:11], v[154:155], v[204:205], v[22:23] op_sel_hi:[1,0,1] neg_lo:[1,0,0] neg_hi:[1,0,0]
	v_pk_fma_f32 v[20:21], v[148:149], v[204:205], v[20:21] op_sel_hi:[1,0,1]
	v_pk_fma_f32 v[18:19], v[146:147], v[204:205], v[18:19] op_sel_hi:[1,0,1] neg_lo:[1,0,0] neg_hi:[1,0,0]
	v_pk_fma_f32 v[8:9], v[204:205], v[140:141], v[8:9] op_sel_hi:[0,1,1] neg_lo:[1,0,0] neg_hi:[1,0,0]
	v_pk_fma_f32 v[6:7], v[204:205], v[138:139], v[6:7] op_sel_hi:[0,1,1] neg_lo:[1,0,0] neg_hi:[1,0,0]
	v_pk_fma_f32 v[4:5], v[204:205], v[132:133], v[4:5] op_sel_hi:[0,1,1] neg_lo:[1,0,0] neg_hi:[1,0,0]
	v_pk_fma_f32 v[2:3], v[204:205], v[130:131], v[2:3] op_sel_hi:[0,1,1] neg_lo:[1,0,0] neg_hi:[1,0,0]
	v_pk_fma_f32 v[126:127], v[126:127], v[200:201], v[158:159] op_sel_hi:[1,0,1]
	v_pk_fma_f32 v[128:129], v[128:129], v[200:201], v[160:161] op_sel_hi:[1,0,1]
	v_pk_fma_f32 v[122:123], v[122:123], v[200:201], v[150:151] op_sel_hi:[1,0,1]
	v_pk_fma_f32 v[124:125], v[124:125], v[200:201], v[152:153] op_sel_hi:[1,0,1]
	v_pk_fma_f32 v[114:115], v[114:115], v[200:201], v[134:135] op_sel_hi:[1,0,1]
	v_pk_fma_f32 v[116:117], v[116:117], v[200:201], v[136:137] op_sel_hi:[1,0,1]
	v_pk_fma_f32 v[106:107], v[106:107], v[200:201], v[158:159] op_sel:[0,1,0]
	v_pk_fma_f32 v[108:109], v[108:109], v[200:201], v[160:161] op_sel:[0,1,0]
	v_pk_fma_f32 v[110:111], v[110:111], v[200:201], v[150:151] op_sel:[0,1,0]
	v_pk_fma_f32 v[112:113], v[112:113], v[200:201], v[152:153] op_sel:[0,1,0]
	v_pk_fma_f32 v[94:95], v[94:95], v[200:201], v[134:135] op_sel:[0,1,0]
	v_pk_fma_f32 v[96:97], v[96:97], v[200:201], v[136:137] op_sel:[0,1,0]
	v_pk_fma_f32 v[90:91], v[90:91], v[198:199], v[158:159] op_sel_hi:[1,0,1]
	v_pk_fma_f32 v[92:93], v[92:93], v[198:199], v[160:161] op_sel_hi:[1,0,1]
	v_pk_fma_f32 v[98:99], v[98:99], v[198:199], v[150:151] op_sel_hi:[1,0,1]
	v_pk_fma_f32 v[100:101], v[100:101], v[198:199], v[152:153] op_sel_hi:[1,0,1]
	v_pk_fma_f32 v[78:79], v[78:79], v[198:199], v[134:135] op_sel_hi:[1,0,1]
	v_pk_fma_f32 v[80:81], v[80:81], v[198:199], v[136:137] op_sel_hi:[1,0,1]
	v_pk_fma_f32 v[74:75], v[74:75], v[198:199], v[158:159] op_sel:[0,1,0]
	v_pk_fma_f32 v[76:77], v[76:77], v[198:199], v[160:161] op_sel:[0,1,0]
	v_pk_fma_f32 v[82:83], v[82:83], v[198:199], v[150:151] op_sel:[0,1,0]
	v_pk_fma_f32 v[84:85], v[84:85], v[198:199], v[152:153] op_sel:[0,1,0]
	v_pk_fma_f32 v[70:71], v[70:71], v[198:199], v[134:135] op_sel:[0,1,0]
	v_pk_fma_f32 v[72:73], v[72:73], v[198:199], v[136:137] op_sel:[0,1,0]
	v_pk_fma_f32 v[66:67], v[66:67], v[198:199], v[142:143] op_sel:[0,1,0]
	v_pk_fma_f32 v[68:69], v[68:69], v[198:199], v[144:145] op_sel:[0,1,0]
	v_pk_fma_f32 v[62:63], v[62:63], v[206:207], v[158:159] op_sel_hi:[1,0,1]
	v_pk_fma_f32 v[64:65], v[64:65], v[206:207], v[160:161] op_sel_hi:[1,0,1]
	v_pk_fma_f32 v[58:59], v[58:59], v[206:207], v[150:151] op_sel_hi:[1,0,1]
	v_pk_fma_f32 v[60:61], v[60:61], v[206:207], v[152:153] op_sel_hi:[1,0,1]
	v_pk_fma_f32 v[46:47], v[46:47], v[206:207], v[134:135] op_sel_hi:[1,0,1]
	v_pk_fma_f32 v[48:49], v[48:49], v[206:207], v[136:137] op_sel_hi:[1,0,1]
	v_pk_fma_f32 v[42:43], v[42:43], v[206:207], v[158:159] op_sel:[0,1,0]
	v_pk_fma_f32 v[44:45], v[44:45], v[206:207], v[160:161] op_sel:[0,1,0]
	v_pk_fma_f32 v[50:51], v[50:51], v[206:207], v[150:151] op_sel:[0,1,0]
	v_pk_fma_f32 v[52:53], v[52:53], v[206:207], v[152:153] op_sel:[0,1,0]
	v_pk_fma_f32 v[34:35], v[34:35], v[206:207], v[134:135] op_sel:[0,1,0]
	v_pk_fma_f32 v[36:37], v[36:37], v[206:207], v[136:137] op_sel:[0,1,0]
	v_pk_fma_f32 v[26:27], v[26:27], v[212:213], v[158:159] op_sel_hi:[1,0,1]
	v_pk_fma_f32 v[28:29], v[28:29], v[212:213], v[160:161] op_sel_hi:[1,0,1]
	v_pk_fma_f32 v[30:31], v[30:31], v[212:213], v[150:151] op_sel_hi:[1,0,1]
	v_pk_fma_f32 v[32:33], v[32:33], v[212:213], v[152:153] op_sel_hi:[1,0,1]
	v_pk_fma_f32 v[14:15], v[14:15], v[212:213], v[134:135] op_sel_hi:[1,0,1]
	v_pk_fma_f32 v[16:17], v[16:17], v[212:213], v[136:137] op_sel_hi:[1,0,1]
	v_pk_fma_f32 v[10:11], v[10:11], v[212:213], v[158:159] op_sel:[0,1,0]
	v_pk_fma_f32 v[12:13], v[12:13], v[212:213], v[160:161] op_sel:[0,1,0]
	v_pk_fma_f32 v[18:19], v[18:19], v[212:213], v[150:151] op_sel:[0,1,0]
	v_pk_fma_f32 v[20:21], v[20:21], v[212:213], v[152:153] op_sel:[0,1,0]
	v_pk_fma_f32 v[6:7], v[6:7], v[212:213], v[134:135] op_sel:[0,1,0]
	v_pk_fma_f32 v[8:9], v[8:9], v[212:213], v[136:137] op_sel:[0,1,0]
	v_pk_fma_f32 v[2:3], v[2:3], v[212:213], v[142:143] op_sel:[0,1,0]
	v_pk_fma_f32 v[4:5], v[4:5], v[212:213], v[144:145] op_sel:[0,1,0]
	s_mov_b64 s[50:51], -1
	s_cmp_gt_i32 s74, 9
	v_ashrrev_i32_e32 v187, 31, v186
	s_mov_b64 s[52:53], 0x2000
	s_cbranch_scc0 .LBB0_205
; #define GAS __attribute__((address_space(1)))
;     __device__ __forceinline__ void operator()(f32x4 (&acc)[2][2][4][2], const Unit& u, int wr, int wc, int fr, int fq) const {
;     ...
;             const int colb = (u.pn - 10) * BM + wc * 32 + 8 * fq;
; #pragma unroll
;             for (int ai = 0; ai < 2; ++ai)
; #pragma unroll
;                 for (int m = 0; m < 4; ++m) { const int row = row0 + ai * HALF + m * 16;
; #pragma unroll
;                     for (int bj = 0; bj < 2; ++bj)
; #pragma unroll
;                         for (int n = 0; n < 2; ++n)
; #pragma unroll
;                             for (int j = 0; j < 4; ++j) *(GAS h16*)(vT + (size_t)(colb + bj * HALF + 4 * n + j) * NT + row) = (h16)acc[ai][bj][m][n][j];
;                     asm volatile("" ::: "memory"); }
	v_and_b32_e32 v134, 15, v221
	v_lshrrev_b32_e32 v135, 4, v221
	v_lshrrev_b32_e32 v136, 6, v252
	v_lshlrev_b32_e32 v136, 11, v136
	v_lshl_add_u32 v136, v135, 9, v136
	v_add_u32_e32 v136, 0x20010, v136
	v_lshl_add_u32 v130, v134, 1, v136
	v_lshl_add_u32 v131, v134, 5, v136
	v_add_u32_e32 v137, s35, v219
	v_lshrrev_b32_e32 v138, 3, v134
	v_and_b32_e32 v139, 7, v134
	v_lshl_add_u32 v137, v138, 7, v137
	v_add_u32_e32 v137, v137, v139
	v_sub_u32_e32 v138, v186, v134
	v_lshlrev_b32_e32 v138, 1, v138
	v_lshl_add_u32 v138, v137, 15, v138
	v_mov_b32_e32 v139, 0
	v_lshl_add_u64 v[132:133], v[138:139], 0, s[12:13]
	v_cvt_f16_f32_e32 v140, v126
	ds_write_b16 v130, v140
	v_cvt_f16_f32_e32 v141, v127
	ds_write_b16 v130, v141 offset:32
	v_cvt_f16_f32_e32 v142, v128
	ds_write_b16 v130, v142 offset:64
	v_cvt_f16_f32_e32 v143, v129
	ds_write_b16 v130, v143 offset:96
	v_cvt_f16_f32_e32 v144, v122
	ds_write_b16 v130, v144 offset:128
	v_cvt_f16_f32_e32 v145, v123
	ds_write_b16 v130, v145 offset:160
	v_cvt_f16_f32_e32 v146, v124
	ds_write_b16 v130, v146 offset:192
	v_cvt_f16_f32_e32 v147, v125
	ds_write_b16 v130, v147 offset:224
	v_cvt_f16_f32_e32 v140, v114
	ds_write_b16 v130, v140 offset:256
	v_cvt_f16_f32_e32 v141, v115
	ds_write_b16 v130, v141 offset:288
	v_cvt_f16_f32_e32 v142, v116
	ds_write_b16 v130, v142 offset:320
	v_cvt_f16_f32_e32 v143, v117
	ds_write_b16 v130, v143 offset:352
	v_cvt_f16_f32_e32 v144, v188
	ds_write_b16 v130, v144 offset:384
	v_cvt_f16_f32_e32 v145, v189
	ds_write_b16 v130, v145 offset:416
	v_cvt_f16_f32_e32 v146, v190
	ds_write_b16 v130, v146 offset:448
	v_cvt_f16_f32_e32 v147, v191
	ds_write_b16 v130, v147 offset:480
	s_waitcnt lgkmcnt(0)
	ds_read_b128 v[150:153], v131
	ds_read_b128 v[154:157], v131 offset:16
	s_waitcnt lgkmcnt(0)
	global_store_dwordx4 v[132:133], v[150:153], off
	global_store_dwordx4 v[132:133], v[154:157], off offset:16
	v_cvt_f16_f32_e32 v140, v106
	ds_write_b16 v130, v140
	v_cvt_f16_f32_e32 v141, v107
	ds_write_b16 v130, v141 offset:32
	v_cvt_f16_f32_e32 v142, v108
	ds_write_b16 v130, v142 offset:64
	v_cvt_f16_f32_e32 v143, v109
	ds_write_b16 v130, v143 offset:96
	v_cvt_f16_f32_e32 v144, v110
	ds_write_b16 v130, v144 offset:128
	v_cvt_f16_f32_e32 v145, v111
	ds_write_b16 v130, v145 offset:160
	v_cvt_f16_f32_e32 v146, v112
	ds_write_b16 v130, v146 offset:192
	v_cvt_f16_f32_e32 v147, v113
	ds_write_b16 v130, v147 offset:224
	v_cvt_f16_f32_e32 v140, v94
	ds_write_b16 v130, v140 offset:256
	v_cvt_f16_f32_e32 v141, v95
	ds_write_b16 v130, v141 offset:288
	v_cvt_f16_f32_e32 v142, v96
	ds_write_b16 v130, v142 offset:320
	v_cvt_f16_f32_e32 v143, v97
	ds_write_b16 v130, v143 offset:352
	v_cvt_f16_f32_e32 v144, v118
	ds_write_b16 v130, v144 offset:384
	v_cvt_f16_f32_e32 v145, v119
	ds_write_b16 v130, v145 offset:416
	v_cvt_f16_f32_e32 v146, v120
	ds_write_b16 v130, v146 offset:448
	v_cvt_f16_f32_e32 v147, v121
	ds_write_b16 v130, v147 offset:480
	s_waitcnt lgkmcnt(0)
	ds_read_b128 v[150:153], v131
	ds_read_b128 v[154:157], v131 offset:16
	s_waitcnt lgkmcnt(0)
	global_store_dwordx4 v[132:133], v[150:153], off offset:32
	global_store_dwordx4 v[132:133], v[154:157], off offset:48
	v_cvt_f16_f32_e32 v140, v90
	ds_write_b16 v130, v140
	v_cvt_f16_f32_e32 v141, v91
	ds_write_b16 v130, v141 offset:32
	v_cvt_f16_f32_e32 v142, v92
	ds_write_b16 v130, v142 offset:64
	v_cvt_f16_f32_e32 v143, v93
	ds_write_b16 v130, v143 offset:96
	v_cvt_f16_f32_e32 v144, v98
	ds_write_b16 v130, v144 offset:128
	v_cvt_f16_f32_e32 v145, v99
	ds_write_b16 v130, v145 offset:160
	v_cvt_f16_f32_e32 v146, v100
	ds_write_b16 v130, v146 offset:192
	v_cvt_f16_f32_e32 v147, v101
	ds_write_b16 v130, v147 offset:224
	v_cvt_f16_f32_e32 v140, v78
	ds_write_b16 v130, v140 offset:256
	v_cvt_f16_f32_e32 v141, v79
	ds_write_b16 v130, v141 offset:288
	v_cvt_f16_f32_e32 v142, v80
	ds_write_b16 v130, v142 offset:320
	v_cvt_f16_f32_e32 v143, v81
	ds_write_b16 v130, v143 offset:352
	v_cvt_f16_f32_e32 v144, v102
	ds_write_b16 v130, v144 offset:384
	v_cvt_f16_f32_e32 v145, v103
	ds_write_b16 v130, v145 offset:416
	v_cvt_f16_f32_e32 v146, v104
	ds_write_b16 v130, v146 offset:448
	v_cvt_f16_f32_e32 v147, v105
	ds_write_b16 v130, v147 offset:480
	s_waitcnt lgkmcnt(0)
	ds_read_b128 v[150:153], v131
	ds_read_b128 v[154:157], v131 offset:16
	s_waitcnt lgkmcnt(0)
	global_store_dwordx4 v[132:133], v[150:153], off offset:64
	global_store_dwordx4 v[132:133], v[154:157], off offset:80
	v_cvt_f16_f32_e32 v140, v74
	ds_write_b16 v130, v140
	v_cvt_f16_f32_e32 v141, v75
	ds_write_b16 v130, v141 offset:32
	v_cvt_f16_f32_e32 v142, v76
	ds_write_b16 v130, v142 offset:64
	v_cvt_f16_f32_e32 v143, v77
	ds_write_b16 v130, v143 offset:96
	v_cvt_f16_f32_e32 v144, v82
	ds_write_b16 v130, v144 offset:128
	v_cvt_f16_f32_e32 v145, v83
	ds_write_b16 v130, v145 offset:160
	v_cvt_f16_f32_e32 v146, v84
	ds_write_b16 v130, v146 offset:192
	v_cvt_f16_f32_e32 v147, v85
	ds_write_b16 v130, v147 offset:224
	v_cvt_f16_f32_e32 v140, v70
	ds_write_b16 v130, v140 offset:256
	v_cvt_f16_f32_e32 v141, v71
	ds_write_b16 v130, v141 offset:288
	v_cvt_f16_f32_e32 v142, v72
	ds_write_b16 v130, v142 offset:320
	v_cvt_f16_f32_e32 v143, v73
	ds_write_b16 v130, v143 offset:352
	v_cvt_f16_f32_e32 v144, v66
	ds_write_b16 v130, v144 offset:384
	v_cvt_f16_f32_e32 v145, v67
	ds_write_b16 v130, v145 offset:416
	v_cvt_f16_f32_e32 v146, v68
	ds_write_b16 v130, v146 offset:448
	v_cvt_f16_f32_e32 v147, v69
	ds_write_b16 v130, v147 offset:480
	s_waitcnt lgkmcnt(0)
; #define GAS __attribute__((address_space(1)))
;     __device__ __forceinline__ void operator()(f32x4 (&acc)[2][2][4][2], const Unit& u, int wr, int wc, int fr, int fq) const {
;     ...
;             const int colb = (u.pn - 10) * BM + wc * 32 + 8 * fq;
; #pragma unroll
;             for (int ai = 0; ai < 2; ++ai)
; #pragma unroll
;                 for (int m = 0; m < 4; ++m) { const int row = row0 + ai * HALF + m * 16;
; #pragma unroll
;                     for (int bj = 0; bj < 2; ++bj)
; #pragma unroll
;                         for (int n = 0; n < 2; ++n)
; #pragma unroll
;                             for (int j = 0; j < 4; ++j) *(GAS h16*)(vT + (size_t)(colb + bj * HALF + 4 * n + j) * NT + row) = (h16)acc[ai][bj][m][n][j];
;                     asm volatile("" ::: "memory"); }
	ds_read_b128 v[150:153], v131
	ds_read_b128 v[154:157], v131 offset:16
	s_waitcnt lgkmcnt(0)
	global_store_dwordx4 v[132:133], v[150:153], off offset:96
	global_store_dwordx4 v[132:133], v[154:157], off offset:112
	v_cvt_f16_f32_e32 v140, v62
	ds_write_b16 v130, v140
	v_cvt_f16_f32_e32 v141, v63
	ds_write_b16 v130, v141 offset:32
	v_cvt_f16_f32_e32 v142, v64
	ds_write_b16 v130, v142 offset:64
	v_cvt_f16_f32_e32 v143, v65
	ds_write_b16 v130, v143 offset:96
	v_cvt_f16_f32_e32 v144, v58
	ds_write_b16 v130, v144 offset:128
	v_cvt_f16_f32_e32 v145, v59
	ds_write_b16 v130, v145 offset:160
	v_cvt_f16_f32_e32 v146, v60
	ds_write_b16 v130, v146 offset:192
	v_cvt_f16_f32_e32 v147, v61
	ds_write_b16 v130, v147 offset:224
	v_cvt_f16_f32_e32 v140, v46
	ds_write_b16 v130, v140 offset:256
	v_cvt_f16_f32_e32 v141, v47
	ds_write_b16 v130, v141 offset:288
	v_cvt_f16_f32_e32 v142, v48
	ds_write_b16 v130, v142 offset:320
	v_cvt_f16_f32_e32 v143, v49
	ds_write_b16 v130, v143 offset:352
	v_cvt_f16_f32_e32 v144, v86
	ds_write_b16 v130, v144 offset:384
	v_cvt_f16_f32_e32 v145, v87
	ds_write_b16 v130, v145 offset:416
	v_cvt_f16_f32_e32 v146, v88
	ds_write_b16 v130, v146 offset:448
	v_cvt_f16_f32_e32 v147, v89
	ds_write_b16 v130, v147 offset:480
	s_waitcnt lgkmcnt(0)
	ds_read_b128 v[150:153], v131
	ds_read_b128 v[154:157], v131 offset:16
	s_waitcnt lgkmcnt(0)
	global_store_dwordx4 v[132:133], v[150:153], off offset:256
	global_store_dwordx4 v[132:133], v[154:157], off offset:272
	v_cvt_f16_f32_e32 v140, v42
	ds_write_b16 v130, v140
	v_cvt_f16_f32_e32 v141, v43
	ds_write_b16 v130, v141 offset:32
	v_cvt_f16_f32_e32 v142, v44
	ds_write_b16 v130, v142 offset:64
	v_cvt_f16_f32_e32 v143, v45
	ds_write_b16 v130, v143 offset:96
	v_cvt_f16_f32_e32 v144, v50
	ds_write_b16 v130, v144 offset:128
	v_cvt_f16_f32_e32 v145, v51
	ds_write_b16 v130, v145 offset:160
	v_cvt_f16_f32_e32 v146, v52
	ds_write_b16 v130, v146 offset:192
	v_cvt_f16_f32_e32 v147, v53
	ds_write_b16 v130, v147 offset:224
	v_cvt_f16_f32_e32 v140, v34
	ds_write_b16 v130, v140 offset:256
	v_cvt_f16_f32_e32 v141, v35
	ds_write_b16 v130, v141 offset:288
	v_cvt_f16_f32_e32 v142, v36
	ds_write_b16 v130, v142 offset:320
	v_cvt_f16_f32_e32 v143, v37
	ds_write_b16 v130, v143 offset:352
	v_cvt_f16_f32_e32 v144, v54
	ds_write_b16 v130, v144 offset:384
	v_cvt_f16_f32_e32 v145, v55
	ds_write_b16 v130, v145 offset:416
	v_cvt_f16_f32_e32 v146, v56
	ds_write_b16 v130, v146 offset:448
	v_cvt_f16_f32_e32 v147, v57
	ds_write_b16 v130, v147 offset:480
	s_waitcnt lgkmcnt(0)
	ds_read_b128 v[150:153], v131
	ds_read_b128 v[154:157], v131 offset:16
	s_waitcnt lgkmcnt(0)
	global_store_dwordx4 v[132:133], v[150:153], off offset:288
	global_store_dwordx4 v[132:133], v[154:157], off offset:304
	v_cvt_f16_f32_e32 v140, v26
	ds_write_b16 v130, v140
	v_cvt_f16_f32_e32 v141, v27
	ds_write_b16 v130, v141 offset:32
	v_cvt_f16_f32_e32 v142, v28
	ds_write_b16 v130, v142 offset:64
	v_cvt_f16_f32_e32 v143, v29
	ds_write_b16 v130, v143 offset:96
	v_cvt_f16_f32_e32 v144, v30
	ds_write_b16 v130, v144 offset:128
	v_cvt_f16_f32_e32 v145, v31
	ds_write_b16 v130, v145 offset:160
	v_cvt_f16_f32_e32 v146, v32
	ds_write_b16 v130, v146 offset:192
	v_cvt_f16_f32_e32 v147, v33
	ds_write_b16 v130, v147 offset:224
	v_cvt_f16_f32_e32 v140, v14
	ds_write_b16 v130, v140 offset:256
	v_cvt_f16_f32_e32 v141, v15
	ds_write_b16 v130, v141 offset:288
	v_cvt_f16_f32_e32 v142, v16
	ds_write_b16 v130, v142 offset:320
	v_cvt_f16_f32_e32 v143, v17
	ds_write_b16 v130, v143 offset:352
	v_cvt_f16_f32_e32 v144, v38
	ds_write_b16 v130, v144 offset:384
	v_cvt_f16_f32_e32 v145, v39
	ds_write_b16 v130, v145 offset:416
	v_cvt_f16_f32_e32 v146, v40
	ds_write_b16 v130, v146 offset:448
	v_cvt_f16_f32_e32 v147, v41
	ds_write_b16 v130, v147 offset:480
	s_waitcnt lgkmcnt(0)
	ds_read_b128 v[150:153], v131
	ds_read_b128 v[154:157], v131 offset:16
	s_waitcnt lgkmcnt(0)
	global_store_dwordx4 v[132:133], v[150:153], off offset:320
	global_store_dwordx4 v[132:133], v[154:157], off offset:336
	v_cvt_f16_f32_e32 v140, v10
	ds_write_b16 v130, v140
	v_cvt_f16_f32_e32 v141, v11
	ds_write_b16 v130, v141 offset:32
	v_cvt_f16_f32_e32 v142, v12
	ds_write_b16 v130, v142 offset:64
	v_cvt_f16_f32_e32 v143, v13
	ds_write_b16 v130, v143 offset:96
	v_cvt_f16_f32_e32 v144, v18
	ds_write_b16 v130, v144 offset:128
	v_cvt_f16_f32_e32 v145, v19
	ds_write_b16 v130, v145 offset:160
	v_cvt_f16_f32_e32 v146, v20
	ds_write_b16 v130, v146 offset:192
	v_cvt_f16_f32_e32 v147, v21
	ds_write_b16 v130, v147 offset:224
	v_cvt_f16_f32_e32 v140, v6
	ds_write_b16 v130, v140 offset:256
	v_cvt_f16_f32_e32 v141, v7
	ds_write_b16 v130, v141 offset:288
	v_cvt_f16_f32_e32 v142, v8
	ds_write_b16 v130, v142 offset:320
	v_cvt_f16_f32_e32 v143, v9
	ds_write_b16 v130, v143 offset:352
	v_cvt_f16_f32_e32 v144, v2
	ds_write_b16 v130, v144 offset:384
	v_cvt_f16_f32_e32 v145, v3
	ds_write_b16 v130, v145 offset:416
	v_cvt_f16_f32_e32 v146, v4
	ds_write_b16 v130, v146 offset:448
	v_cvt_f16_f32_e32 v147, v5
	ds_write_b16 v130, v147 offset:480
	s_waitcnt lgkmcnt(0)
	ds_read_b128 v[150:153], v131
	ds_read_b128 v[154:157], v131 offset:16
	s_waitcnt lgkmcnt(0)
	global_store_dwordx4 v[132:133], v[150:153], off offset:352
	global_store_dwordx4 v[132:133], v[154:157], off offset:368
	s_mov_b64 s[50:51], 0
